# split seam: early look at the global round during the invalidate so late panels skip the epilogue check
# baseline (speedup 1.0000x reference)
; __device__ __forceinline__ unsigned xb_ld(unsigned* p)              { return __hip_atomic_load(p, __ATOMIC_RELAXED, __HIP_MEMORY_SCOPE_AGENT); }
; __device__ __forceinline__ unsigned xb_add(unsigned* p, unsigned v) { return __hip_atomic_fetch_add(p, v, __ATOMIC_RELAXED, __HIP_MEMORY_SCOPE_AGENT); }
; #define XB_SPIN(cond, bar) do { unsigned _sp = 0; while (cond) { __builtin_amdgcn_s_sleep(1); \
;     if ((++_sp & 255u) == 0u) { if (xb_ld(&(bar)[XB_TMO])) break; if (_sp > XB_SPIN_CAP) { atomicAdd(&(bar)[XB_TMO], 1u); break; } } } } while (0)
; __device__ __forceinline__ void xcd_barrier(const XcdBarrier& b) {
;     ...
;             __builtin_amdgcn_fence(__ATOMIC_ACQUIRE, "agent");
;             xb_add(&bar[XB_XGEN(b.x)], 1u);
;             asm volatile("s_waitcnt vmcnt(0)" ::: "memory");
;         } else {
;             XB_SPIN(xb_ld(&bar[XB_XGEN(b.x)]) == gen, bar);
;             __builtin_amdgcn_fence(__ATOMIC_ACQUIRE, "agent");
;             asm volatile("s_waitcnt vmcnt(0)" ::: "memory");
;         }
.Lgb2_gacq:
	s_lshl_b32 s10, s33, 8
	s_add_i32 s10, s10, 0x10000
	v_mov_b32_e32 v5, s10
	global_load_dword v5, v5, s[46:47] sc1
	buffer_inv sc1
	s_waitcnt vmcnt(0)
	v_readfirstlane_b32 s14, v5
	s_cmp_ge_u32 s14, s101
	s_cselect_b32 s101, 0, s101
	s_mov_b64 exec, s[8:9]
